# phase 9 (dwconv+gelu) items spread over all 256 workgroups (358 per workgroup) instead of 512 per workgroup on 179
# speedup vs baseline: 1.1209x; 1.0045x over previous
.LBB0_178:
	s_andn2_b64 vcc, exec, s[0:1]
	s_cbranch_vccnz .LBB0_219
	v_readlane_b32 s0, v250, 15
	s_waitcnt vmcnt(0)
	s_nop 0
	v_readlane_b32 s0, v255, 13
	s_nop 3
	s_mul_i32 s0, s0, 0x166
	v_add_u32_e32 v98, s0, v166
	s_mov_b32 s0, 0x16580
	v_cmp_gt_i32_e32 vcc, s0, v98
	s_movk_i32 s0, 0x166
	v_cmp_gt_u32_e64 s[0:1], s0, v166
	s_and_b64 vcc, vcc, s[0:1]
	s_and_saveexec_b64 s[40:41], vcc
	s_cbranch_execz .LBB0_218
	s_mov_b64 s[42:43], 0
	s_branch .LBB0_182
